# code placement: attention inner-loop heads aligned to 64 bytes (timing-only)
# baseline (speedup 1.0000x reference)
; #define LAS __attribute__((address_space(3)))
; __device__ __forceinline__ int my_tid() { int t = threadIdx.x; asm volatile("" : "+v"(t)); return t; }
; __device__ __forceinline__ int v_st(int k, int c) { const int kk = (k & ~0xC) | ((k & 4) << 1) | ((k & 8) >> 1); return ((kk >> 3) * 4 + (c >> 5)) * 512 + ((kk & 7) * 32 + (c & 31)) * 2; }
; __device__ __forceinline__ int v_rd_base(int lane) { return ((lane & 3) << 3) | (((lane >> 2) & 3) << 6) | (((lane >> 4) & 1) << 5) | (((lane >> 5) & 1) << 8); }
; template <int NDQ, int NDV> ...
;   const int tid = my_tid(), wid = tid >> 6, lane = tid & 63, r32 = lane & 31, hi = lane >> 5;
;   LP V_lds = lds; LP K_lds = lds + 2 * SHM_V;
;   LAS float* wsx = (LAS float*)(lds + 2 * SHM_V + 2 * SHM_K) + wid * 64; LAS float* li_l = wsx; LAS float* al_l = wsx + 32;
;   float m_reg = -1e30f, l_reg = 0; f32x16 o[NDV]; bf16x8 qr[NDQ];
; #pragma unroll
;   for (int d = 0; d < NDV; ++d) o[d] = f32x16{};
;   const bf16_t* Qw = Qb + (size_t)(wid * 32 + r32) * ldq + hi * 8;
; #pragma unroll
;   for (int d0 = 0; d0 < NDQ; ++d0) qr[d0] = *reinterpret_cast<const bf16x8*>(Qw + d0 * 16);
;   const int sr = tid >> 4, sc = (tid & 15) * 8, vst0 = v_st(sr, sc), vst1 = v_st(32 + sr, sc);
;   const int vb0 = (int)(unsigned)(size_t)V_lds + v_rd_base(lane);
;   struct { bf16x8 vs0, vs1, ks0, ks1; } sr_[2];
;     ...
;   f32x16 pA0, pA1, pB0, pB1; float mnA, mnB, alA, alB; bf16x8 pa0, pa1, pa2, pa3; const int NT = seq / 64;
;   constexpr int SE = 0, SO = 1;
;   __syncthreads();
;   SLOAD(SE, 0); asm volatile("s_waitcnt vmcnt(0)" ::: "memory"); SWRITE(0, SE); __syncthreads();
;   qkt<NDQ>(pA0, pA1, K_lds, qr, r32, hi); partialSM(pA0, pA1, m_reg, mnA, alA, Cs, thr);
; __device__ __forceinline__ void phase_mix0(const Params& p, LP lds) {
;     ...
;     const size_t kb = (size_t)b * TPB;
;     const bf16_t* kptr = sc < 64 ? KV + kb * 1024 + h * 128 + sc : KPE + kb * 32 + ((sc - 64) & 31);
;     const int kstr = sc < 64 ? 1024 : 32;
;     const bf16_t* vptr = KV + kb * 1024 + h * 128 + 64 + (sc & 63);
.LBB0_1483:
	s_mul_hi_i32 s5, s9, 0x1080000
	s_mul_i32 s4, s9, 0x1080000
	s_and_saveexec_b64 s[6:7], s[2:3]
	s_xor_b64 s[6:7], exec, s[6:7]
	v_mad_i64_i32 v[150:151], s[10:11], s9, v163, v[138:139]
	s_or_saveexec_b64 s[6:7], s[6:7]
	v_mov_b64_e32 v[48:49], 32
	v_mov_b64_e32 v[50:51], s[4:5]
	s_xor_b64 exec, exec, s[6:7]
	v_mad_i64_i32 v[150:151], s[10:11], s9, v164, v[140:141]
	v_mov_b64_e32 v[48:49], 0x400
	v_mov_b64_e32 v[50:51], s[4:5]
	s_or_b64 exec, exec, s[6:7]
	s_ashr_i32 s31, s30, 31
	s_mul_i32 s4, s30, 0x600
	s_mul_hi_i32 s5, s30, 0x600
	s_add_u32 s4, s27, s4
	v_mov_b32_e32 v49, v190
	s_addc_u32 s5, s35, s5
	v_mov_b64_e32 v[0:1], s[4:5]
	v_ashrrev_i32_e32 v58, 1, v49
	v_ashrrev_i32_e32 v52, 4, v49
	v_bfe_u32 v166, v49, 5, 1
	v_bfi_b32 v2, s42, v58, v49
	v_add_u32_e32 v16, 32, v52
	v_mad_i64_i32 v[0:1], s[4:5], v2, s41, v[0:1]
	v_lshlrev_b32_e32 v146, 4, v166
	v_mov_b32_e32 v147, v137
	v_ashrrev_i32_e32 v53, 31, v52
	v_ashrrev_i32_e32 v17, 31, v16
	v_lshl_add_u64 v[56:57], v[142:143], 0, v[50:51]
	v_lshl_add_u64 v[0:1], v[0:1], 0, v[146:147]
	v_lshlrev_b64 v[54:55], 11, v[52:53]
	v_lshlrev_b64 v[2:3], 11, v[16:17]
	v_mad_i64_i32 v[8:9], s[4:5], v48, v52, 0
	v_mad_i64_i32 v[10:11], s[4:5], v48, v16, 0
	global_load_dwordx4 v[84:87], v[0:1], off
	global_load_dwordx4 v[80:83], v[0:1], off offset:32
	global_load_dwordx4 v[76:79], v[0:1], off offset:64
	global_load_dwordx4 v[72:75], v[0:1], off offset:96
	global_load_dwordx4 v[68:71], v[0:1], off offset:128
	global_load_dwordx4 v[64:67], v[0:1], off offset:160
	v_lshl_add_u64 v[0:1], v[56:57], 0, v[54:55]
	v_lshl_add_u64 v[4:5], v[56:57], 0, v[2:3]
	v_lshl_add_u64 v[8:9], v[8:9], 1, v[150:151]
	v_lshl_add_u64 v[12:13], v[10:11], 1, v[150:151]
	s_waitcnt vmcnt(63) expcnt(7) lgkmcnt(15)
	s_barrier
	global_load_dwordx4 v[0:3], v[0:1], off offset:128
	s_nop 0
	global_load_dwordx4 v[4:7], v[4:5], off offset:128
	s_nop 0
	global_load_dwordx4 v[8:11], v[8:9], off
	s_nop 0
	global_load_dwordx4 v[12:15], v[12:13], off
	v_lshlrev_b32_e32 v17, 3, v49
	v_and_b32_e32 v20, 0xfffff0, v52
	v_lshlrev_b32_e32 v21, 1, v52
	v_lshrrev_b32_e32 v22, 1, v52
	v_and_b32_e32 v23, 3, v52
	v_and_b32_e32 v19, 0x78, v17
	v_and_or_b32 v20, v21, 8, v20
	v_and_or_b32 v21, v22, 4, v23
	v_and_b32_e32 v22, 0xfffff0, v16
	v_lshlrev_b32_e32 v23, 1, v16
	v_and_b32_e32 v18, 0xf0, v49
	v_bfe_u32 v17, v17, 5, 2
	v_lshlrev_b32_e32 v24, 8, v52
	v_lshlrev_b32_e32 v19, 1, v19
	v_lshlrev_b32_e32 v16, 8, v16
	v_lshrrev_b32_e32 v20, 1, v20
	v_and_or_b32 v22, v23, 8, v22
	s_waitcnt vmcnt(11)
	v_and_b32_e32 v26, 48, v19
	v_bitop3_b32 v23, v19, v24, v18 bitop3:0xde
	v_bitop3_b32 v16, v19, v16, v18 bitop3:0xde
	v_or_b32_e32 v18, v20, v17
	v_lshrrev_b32_e32 v19, 1, v22
	v_and_b32_e32 v147, 31, v49
	v_lshlrev_b32_e32 v53, 4, v49
	v_lshlrev_b32_e32 v21, 6, v21
	v_add_u32_e32 v172, 0, v16
	v_lshlrev_b32_e32 v16, 9, v18
	v_or_b32_e32 v17, v19, v17
	v_lshl_add_u32 v62, v147, 8, 0
	v_bitop3_b32 v25, v146, v53, s38 bitop3:0x78
	v_or3_b32 v16, v16, v21, v26
	v_lshlrev_b32_e32 v17, 9, v17
	v_or3_b32 v17, v17, v21, v26
	v_add_u32_e32 v173, 0, v16
	v_add_u32_e32 v175, v62, v25
	v_add_u32_e32 v171, 0, v23
	s_waitcnt vmcnt(0)
	v_add_u32_e32 v174, 0, v17
	v_and_b32_e32 v121, 63, v49
	v_and_b32_e32 v148, 0xffffffe0, v58
	v_add_u32_e32 v96, 0x80, v52
	v_ashrrev_i32_e32 v97, 31, v96
	s_mov_b32 s9, s8
	s_mov_b32 s10, s8
	s_mov_b32 s11, s8
	s_mov_b32 s12, s8
	s_mov_b32 s13, s8
	s_mov_b32 s14, s8
	s_mov_b32 s15, s8
	s_mov_b32 s16, s8
	s_waitcnt vmcnt(3)
	ds_write_b128 v173, v[0:3]
	s_waitcnt vmcnt(2)
	ds_write_b128 v174, v[4:7]
	s_waitcnt vmcnt(1)
	ds_write_b128 v171, v[8:11] offset:32768
	s_waitcnt vmcnt(0)
	ds_write_b128 v172, v[12:15] offset:32768
	s_waitcnt lgkmcnt(0)
	s_barrier
	ds_read_b128 v[0:3], v175 offset:32768
	ds_read_b128 v[4:7], v175 offset:40960
	s_waitcnt lgkmcnt(1)
	v_mfma_f32_32x32x16_bf16 v[32:47], v[0:3], v[84:87], 0
	v_and_b32_e32 v12, 0xf0, v53
	v_bitop3_b32 v0, v146, v12, 32 bitop3:0x36
	v_add_u32_e32 v176, v62, v0
	v_and_b32_e32 v8, 0x3fffffc0, v49
	v_lshl_add_u32 v149, v8, 2, s74
	v_add_u32_e32 v8, 0x60, v52
	v_ashrrev_i32_e32 v9, 31, v8
	s_waitcnt lgkmcnt(0)
	v_mfma_f32_32x32x16_bf16 v[16:31], v[4:7], v[84:87], 0
	ds_read_b128 v[0:3], v176 offset:32768
	ds_read_b128 v[4:7], v176 offset:40960
	v_lshlrev_b64 v[10:11], 11, v[8:9]
	v_lshl_add_u64 v[10:11], v[56:57], 0, v[10:11]
	v_lshlrev_b32_e32 v13, 3, v121
	v_and_b32_e32 v14, 0xc0, v53
	s_mov_b32 s17, s8
	s_mov_b32 s18, s8
	s_waitcnt lgkmcnt(1)
	v_mfma_f32_32x32x16_bf16 v[32:47], v[0:3], v[80:83], v[32:47]
	v_bitop3_b32 v0, v146, v12, 64 bitop3:0x36
	v_add_u32_e32 v177, v62, v0
	s_mov_b32 s19, s8
	s_mov_b32 s20, s8
	s_mov_b32 s21, s8
	s_mov_b32 s22, s8
	s_mov_b32 s23, s8
	s_waitcnt lgkmcnt(0)
	v_mfma_f32_32x32x16_bf16 v[16:31], v[4:7], v[80:83], v[16:31]
	ds_read_b128 v[0:3], v177 offset:32768
	ds_read_b128 v[4:7], v177 offset:40960
	s_mov_b32 s57, 4
	v_lshl_add_u32 v167, v147, 2, v149
	v_lshlrev_b32_e32 v136, 8, v48
	v_mov_b32_e32 v169, 0
	s_waitcnt lgkmcnt(1)
	v_mfma_f32_32x32x16_bf16 v[32:47], v[0:3], v[76:79], v[32:47]
	v_bitop3_b32 v0, v146, v12, s43 bitop3:0x36
	v_add_u32_e32 v178, v62, v0
	ds_read_b128 v[0:3], v178 offset:32768
	s_waitcnt lgkmcnt(1)
	v_mfma_f32_32x32x16_bf16 v[16:31], v[4:7], v[76:79], v[16:31]
	ds_read_b128 v[4:7], v178 offset:40960
	s_waitcnt lgkmcnt(1)
	v_mfma_f32_32x32x16_bf16 v[32:47], v[0:3], v[72:75], v[32:47]
	v_bitop3_b32 v0, v146, v12, s44 bitop3:0x36
	v_add_u32_e32 v179, v62, v0
	ds_read_b128 v[0:3], v179 offset:32768
	s_waitcnt lgkmcnt(1)
; #define SLOAD(i, k0) do { sr_[i].vs0 = *reinterpret_cast<const bf16x8*>(vptr + (size_t)((k0) + sr) * vstr); \
;     sr_[i].vs1 = *reinterpret_cast<const bf16x8*>(vptr + (size_t)((k0) + 32 + sr) * vstr); \
;     sr_[i].ks0 = *reinterpret_cast<const bf16x8*>(kptr + (size_t)((k0) + sr) * kstr); \
;     sr_[i].ks1 = *reinterpret_cast<const bf16x8*>(kptr + (size_t)((k0) + 32 + sr) * kstr); } while (0)
; #define SWRITE(b, i) do { *(LAS bf16x8*)(V_lds + (b) * SHM_V + vst0) = sr_[i].vs0;          \
;     *(LAS bf16x8*)(V_lds + (b) * SHM_V + vst1) = sr_[i].vs1; const int kc = sc * 2;               \
;     *(LAS bf16x8*)(K_lds + (b) * SHM_K + KSWZ(sr, kc)) = sr_[i].ks0;                       \
;     *(LAS bf16x8*)(K_lds + (b) * SHM_K + KSWZ(32 + sr, kc)) = sr_[i].ks1; } while (0)
; #define SWAIT() asm volatile("s_waitcnt vmcnt(4)" ::: "memory")
; __device__ __forceinline__ void partialSM(f32x16& p0, f32x16& p1, float& m_reg, float& mn, float& alpha, float C, float thr) {
;   float pmax = p0[0];
; #pragma unroll
;   for (int r = 1; r < 16; ++r) pmax = fmaxf(pmax, p0[r]);
; #pragma unroll
;   for (int r = 0; r < 16; ++r) pmax = fmaxf(pmax, p1[r]);
;   { auto rr = __builtin_amdgcn_permlane32_swap(__float_as_uint(pmax), __float_as_uint(pmax), false, false);
;     pmax = fmaxf(__uint_as_float(rr[0]), __uint_as_float(rr[1])); }
;   if (__builtin_expect(__all(pmax - m_reg <= thr), 1)) { mn = m_reg; alpha = 1.f; }
;   else { mn = fmaxf(m_reg, pmax); alpha = __builtin_amdgcn_exp2f((m_reg - mn) * C); m_reg = mn; }
;   const float mnC = -mn * C;
; #pragma unroll
;   for (int r = 0; r < 16; ++r) p0[r] = fmaf(p0[r], C, mnC);
; #pragma unroll
;   for (int r = 0; r < 16; ++r) p1[r] = fmaf(p1[r], C, mnC);
; #pragma unroll
;   for (int r = 0; r < 16; ++r) p0[r] = __builtin_amdgcn_exp2f(p0[r]);
; }
; template <int NDQ, int NDV> ...
;     ...
;   qkt<NDQ>(pA0, pA1, K_lds, qr, r32, hi); partialSM(pA0, pA1, m_reg, mnA, alA, Cs, thr);
;   SLOAD(SO, 64); if (2 < NT) SLOAD(SE, 128);
;   SWAIT(); SWRITE(1, SO); __syncthreads();
;   for (int j = 1; j + 1 < NT; j += 2) {
	v_mfma_f32_32x32x16_bf16 v[16:31], v[4:7], v[72:75], v[16:31]
	v_add_u32_e32 v4, 64, v52
	v_ashrrev_i32_e32 v5, 31, v4
	v_lshlrev_b64 v[6:7], 11, v[4:5]
	v_lshl_add_u64 v[6:7], v[56:57], 0, v[6:7]
	v_mad_i64_i32 v[4:5], s[4:5], v48, v4, 0
	global_load_dwordx4 v[58:61], v[6:7], off offset:128
	global_load_dwordx4 v[104:107], v[10:11], off offset:128
	v_lshl_add_u64 v[4:5], v[4:5], 1, v[150:151]
	v_mad_i64_i32 v[6:7], s[4:5], v48, v8, 0
	v_lshl_add_u64 v[6:7], v[6:7], 1, v[150:151]
	global_load_dwordx4 v[108:111], v[4:5], off
	global_load_dwordx4 v[112:115], v[6:7], off
	v_lshlrev_b32_e32 v5, 1, v49
	s_waitcnt lgkmcnt(0)
	v_mfma_f32_32x32x16_bf16 v[32:47], v[0:3], v[68:71], v[32:47]
	v_bitop3_b32 v0, v146, v12, s45 bitop3:0x36
	v_and_or_b32 v4, v13, 24, v14
	v_and_b32_e32 v5, 32, v5
	v_and_b32_e32 v6, 0x100, v13
	v_add_u32_e32 v180, v62, v0
	v_or3_b32 v49, v4, v5, v6
	ds_read_b128 v[4:7], v179 offset:40960
	ds_read_b128 v[0:3], v180 offset:32768
	ds_read_b128 v[88:91], v180 offset:40960
	s_waitcnt lgkmcnt(1)
	v_mfma_f32_32x32x16_bf16 v[32:47], v[0:3], v[64:67], v[32:47]
	v_add_u32_e32 v170, 0, v49
	v_add_u32_e32 v168, s75, v49
	s_nop 9
	v_max_f32_e32 v53, v33, v33
	v_mfma_f32_32x32x16_bf16 v[16:31], v[4:7], v[68:71], v[16:31]
	v_max_f32_e32 v62, v32, v32
	v_max_f32_e32 v53, v62, v53
	v_max3_f32 v53, v53, v34, v35
	v_max3_f32 v53, v53, v36, v37
	v_max3_f32 v53, v53, v38, v39
	v_max3_f32 v53, v53, v40, v41
	v_max3_f32 v53, v53, v42, v43
	s_waitcnt lgkmcnt(0)
	v_mfma_f32_32x32x16_bf16 v[16:31], v[88:91], v[64:67], v[16:31]
	v_max3_f32 v53, v53, v44, v45
	v_max3_f32 v53, v53, v46, v47
	v_mad_i64_i32 v[90:91], s[4:5], v48, v96, 0
	v_lshl_add_u64 v[90:91], v[90:91], 1, v[150:151]
	v_lshlrev_b64 v[96:97], 11, v[96:97]
	v_mov_b64_e32 v[0:1], s[8:9]
	s_nop 5
	v_max3_f32 v53, v53, v16, v17
	v_max3_f32 v53, v53, v18, v19
	v_max3_f32 v53, v53, v20, v21
	v_max3_f32 v53, v53, v22, v23
	v_max3_f32 v53, v53, v24, v25
	v_max3_f32 v53, v53, v26, v27
	v_max3_f32 v53, v53, v28, v29
	v_max3_f32 v53, v53, v30, v31
	v_mov_b32_e32 v62, v53
	s_nop 1
	v_permlane32_swap_b32_e32 v53, v62
	v_max_f32_e32 v62, v62, v62
	v_max_f32_e32 v53, v53, v53
	v_max_f32_e32 v53, v53, v62
	v_add_u32_e32 v62, 0xa0, v52
	v_ashrrev_i32_e32 v63, 31, v62
	v_mad_i64_i32 v[88:89], s[4:5], v48, v62, 0
	v_lshlrev_b64 v[62:63], 11, v[62:63]
	v_lshl_add_u64 v[88:89], v[88:89], 1, v[150:151]
	v_lshl_add_u64 v[62:63], v[56:57], 0, v[62:63]
	global_load_dwordx4 v[92:95], v[88:89], off
	s_nop 0
	global_load_dwordx4 v[88:91], v[90:91], off
	v_lshl_add_u64 v[56:57], v[56:57], 0, v[96:97]
	global_load_dwordx4 v[100:103], v[62:63], off offset:128
	global_load_dwordx4 v[96:99], v[56:57], off offset:128
	v_add_f32_e32 v116, 0x7149f2ca, v53
	v_cmp_ge_f32_e32 vcc, s46, v116
	s_cmp_eq_u64 vcc, exec
	v_max_f32_e32 v53, 0xf149f2ca, v53
	s_cselect_b64 vcc, -1, 0
	v_cndmask_b32_e32 v120, v53, v165, vcc
	v_mul_f32_e32 v56, 0xbe16c740, v120
	v_fmamk_f32 v32, v32, 0x3e16c740, v56
	v_exp_f32_e32 v130, v32
	v_fmamk_f32 v32, v33, 0x3e16c740, v56
	v_exp_f32_e32 v134, v32
	v_fmamk_f32 v32, v34, 0x3e16c740, v56
	v_exp_f32_e32 v131, v32
	v_fmamk_f32 v32, v35, 0x3e16c740, v56
	v_exp_f32_e32 v135, v32
	v_fmamk_f32 v32, v36, 0x3e16c740, v56
	v_exp_f32_e32 v132, v32
	v_fmamk_f32 v32, v37, 0x3e16c740, v56
	v_exp_f32_e32 v185, v32
	v_fmamk_f32 v32, v38, 0x3e16c740, v56
	v_exp_f32_e32 v133, v32
	v_fmamk_f32 v32, v39, 0x3e16c740, v56
	v_exp_f32_e32 v186, v32
	v_fmamk_f32 v32, v40, 0x3e16c740, v56
	v_exp_f32_e32 v122, v32
	v_fmamk_f32 v32, v41, 0x3e16c740, v56
	v_exp_f32_e32 v125, v32
	v_fmamk_f32 v32, v42, 0x3e16c740, v56
	v_exp_f32_e32 v123, v32
	v_fmamk_f32 v32, v43, 0x3e16c740, v56
	v_exp_f32_e32 v126, v32
	v_fmamk_f32 v32, v44, 0x3e16c740, v56
	s_waitcnt vmcnt(4)
	s_waitcnt vmcnt(7)
	ds_write_b128 v173, v[58:61] offset:16384
	s_waitcnt vmcnt(6)
	ds_write_b128 v174, v[104:107] offset:16384
	s_waitcnt vmcnt(5)
	ds_write_b128 v171, v[108:111] offset:49152
	s_waitcnt vmcnt(4)
	ds_write_b128 v172, v[112:115] offset:49152
	v_exp_f32_e32 v124, v32
	v_fmamk_f32 v32, v45, 0x3e16c740, v56
	v_sub_f32_e32 v33, 0xf149f2ca, v53
	v_pk_fma_f32 v[114:115], v[18:19], s[26:27], v[56:57] op_sel_hi:[1,0,0]
	v_pk_fma_f32 v[116:117], v[16:17], s[26:27], v[56:57] op_sel_hi:[1,0,0]
	v_lshlrev_b32_e32 v18, 1, v48
	v_add_u32_e32 v16, 0x120, v52
	v_exp_f32_e32 v127, v32
	v_fmamk_f32 v32, v46, 0x3e16c740, v56
	v_mul_f32_e32 v33, 0x3e16c740, v33
	v_mad_i64_i32 v[152:153], s[6:7], v18, v16, 0
	v_lshl_add_u64 v[16:17], v[50:51], 0, v[54:55]
	v_exp_f32_e32 v33, v33
	v_exp_f32_e32 v128, v32
	v_fmamk_f32 v32, v47, 0x3e16c740, v56
	v_lshl_add_u64 v[154:155], v[144:145], 0, v[16:17]
	v_add_u32_e32 v16, 0x100, v52
	v_exp_f32_e32 v129, v32
	v_mad_i64_i32 v[156:157], s[6:7], v18, v16, 0
	v_add_u32_e32 v16, 0xe0, v52
	v_mov_b64_e32 v[14:15], s[22:23]
	v_mad_i64_i32 v[158:159], s[6:7], v18, v16, 0
	v_add_u32_e32 v16, 0xc0, v52
	v_mov_b64_e32 v[2:3], s[10:11]
	v_mov_b64_e32 v[4:5], s[12:13]
	v_mov_b64_e32 v[6:7], s[14:15]
	v_mov_b64_e32 v[8:9], s[16:17]
	v_mov_b64_e32 v[10:11], s[18:19]
	v_mov_b64_e32 v[12:13], s[20:21]
	v_pk_fma_f32 v[108:109], v[30:31], s[26:27], v[56:57] op_sel_hi:[1,0,0]
	v_pk_fma_f32 v[112:113], v[28:29], s[26:27], v[56:57] op_sel_hi:[1,0,0]
	v_pk_fma_f32 v[118:119], v[26:27], s[26:27], v[56:57] op_sel_hi:[1,0,0]
	v_pk_fma_f32 v[104:105], v[24:25], s[26:27], v[56:57] op_sel_hi:[1,0,0]
	v_pk_fma_f32 v[106:107], v[22:23], s[26:27], v[56:57] op_sel_hi:[1,0,0]
	v_pk_fma_f32 v[110:111], v[20:21], s[26:27], v[56:57] op_sel_hi:[1,0,0]
	v_mad_i64_i32 v[160:161], s[6:7], v18, v16, 0
	v_mov_b64_e32 v[30:31], v[14:15]
	v_cndmask_b32_e64 v181, v33, 1.0, vcc
	v_cmp_gt_u32_e64 s[4:5], 32, v121
	v_mov_b64_e32 v[28:29], v[12:13]
	v_mov_b64_e32 v[26:27], v[10:11]
	v_mov_b64_e32 v[24:25], v[8:9]
	v_mov_b64_e32 v[22:23], v[6:7]
	v_mov_b64_e32 v[20:21], v[4:5]
	v_mov_b64_e32 v[18:19], v[2:3]
	v_mov_b64_e32 v[16:17], v[0:1]
	s_waitcnt lgkmcnt(0)
	s_barrier
	.p2align	6

; #define LAS __attribute__((address_space(3)))
; __device__ __forceinline__ int my_tid() { int t = threadIdx.x; asm volatile("" : "+v"(t)); return t; }
; __device__ __forceinline__ int v_st(int k, int c) { const int kk = (k & ~0xC) | ((k & 4) << 1) | ((k & 8) >> 1); return ((kk >> 3) * 4 + (c >> 5)) * 512 + ((kk & 7) * 32 + (c & 31)) * 2; }
; __device__ __forceinline__ int v_rd_base(int lane) { return ((lane & 3) << 3) | (((lane >> 2) & 3) << 6) | (((lane >> 4) & 1) << 5) | (((lane >> 5) & 1) << 8); }
; template <int NDQ, int NDV> ...
;   const int tid = my_tid(), wid = tid >> 6, lane = tid & 63, r32 = lane & 31, hi = lane >> 5;
;   LP V_lds = lds; LP K_lds = lds + 2 * SHM_V;
;   LAS float* wsx = (LAS float*)(lds + 2 * SHM_V + 2 * SHM_K) + wid * 64; LAS float* li_l = wsx; LAS float* al_l = wsx + 32;
;   float m_reg = -1e30f, l_reg = 0; f32x16 o[NDV]; bf16x8 qr[NDQ];
; #pragma unroll
;   for (int d = 0; d < NDV; ++d) o[d] = f32x16{};
;   const bf16_t* Qw = Qb + (size_t)(wid * 32 + r32) * ldq + hi * 8;
; #pragma unroll
;   for (int d0 = 0; d0 < NDQ; ++d0) qr[d0] = *reinterpret_cast<const bf16x8*>(Qw + d0 * 16);
;   const int sr = tid >> 4, sc = (tid & 15) * 8, vst0 = v_st(sr, sc), vst1 = v_st(32 + sr, sc);
;   const int vb0 = (int)(unsigned)(size_t)V_lds + v_rd_base(lane);
;   struct { bf16x8 vs0, vs1, ks0, ks1; } sr_[2];
;     ...
;   f32x16 pA0, pA1, pB0, pB1; float mnA, mnB, alA, alB; bf16x8 pa0, pa1, pa2, pa3; const int NT = seq / 64;
;   constexpr int SE = 0, SO = 1;
;   __syncthreads();
;   SLOAD(SE, 0); asm volatile("s_waitcnt vmcnt(0)" ::: "memory"); SWRITE(0, SE); __syncthreads();
;   qkt<NDQ>(pA0, pA1, K_lds, qr, r32, hi); partialSM(pA0, pA1, m_reg, mnA, alA, Cs, thr);
; __device__ __forceinline__ void phase_mix1(const Params& p, LP lds) {
;     ...
;     const int blkv = t & 255, rnd = t >> 8, bh = rnd * 8 + (blkv & 7), qb = blkv >> 3, b = bh >> 3, h = bh & 7, kvh = h >> 2;
;     const int row0 = b * TPB + CTXL + qb * 256;
;     const size_t kb = (size_t)b * TPB;
;     attn_body<8, 4>(Q + (size_t)row0 * 1536 + h * 128, 1536, Q + kb * 1536 + 1024 + kvh * 128 + sc, 1536, Q + kb * 1536 + 1280 + kvh * 128 + sc, 1536,
.LBB0_2122:
	s_ashr_i32 s3, s59, 8
	s_lshl_b32 s28, s59, 5
	s_mul_i32 s1, s3, 0x2100
	s_and_b32 s28, s28, 0x1f00
	s_add_i32 s1, s1, s28
	s_add_i32 s28, s1, 0x100
	s_and_b32 s2, s58, 4
	s_and_b32 s0, s59, 7
	s_ashr_i32 s29, s28, 31
	s_mul_i32 s30, s28, 0xc00
	s_mul_hi_i32 s1, s28, 0xc00
	s_add_u32 s30, s5, s30
	s_addc_u32 s1, s35, s1
	s_lshl_b32 s60, s0, 7
	s_lshl_b32 s0, s0, 8
	s_add_u32 s0, s30, s0
	s_addc_u32 s1, s1, 0
	s_mul_i32 s31, s3, 0x18c0000
	s_mul_hi_i32 s30, s3, 0x18c0000
	s_add_u32 s31, s5, s31
	s_addc_u32 s36, s35, s30
	s_lshl_b32 s30, s59, 6
	s_and_b32 s30, s30, 0x100
	v_mov_b32_e32 v58, v190
	s_add_u32 s30, s31, s30
	s_addc_u32 s31, s36, 0
	v_ashrrev_i32_e32 v59, 1, v58
	v_bfe_u32 v188, v58, 5, 1
	v_bfi_b32 v2, s41, v59, v58
	v_mov_b64_e32 v[0:1], s[0:1]
	v_ashrrev_i32_e32 v70, 4, v58
	v_lshl_add_u64 v[48:49], s[30:31], 0, v[180:181]
	v_mad_i64_i32 v[0:1], s[0:1], v2, s40, v[0:1]
	v_lshlrev_b32_e32 v176, 4, v188
	v_add_u32_e32 v16, 32, v70
	v_lshl_add_u64 v[0:1], v[0:1], 0, v[176:177]
	v_mad_i64_i32 v[8:9], s[0:1], v70, s40, v[48:49]
	v_mad_i64_i32 v[12:13], s[0:1], v16, s40, v[48:49]
	global_load_dwordx4 v[124:127], v[0:1], off
	global_load_dwordx4 v[120:123], v[0:1], off offset:32
	global_load_dwordx4 v[116:119], v[0:1], off offset:64
	global_load_dwordx4 v[112:115], v[0:1], off offset:96
	global_load_dwordx4 v[108:111], v[0:1], off offset:128
	global_load_dwordx4 v[104:107], v[0:1], off offset:160
	global_load_dwordx4 v[100:103], v[0:1], off offset:192
	global_load_dwordx4 v[96:99], v[0:1], off offset:224
	s_barrier
	global_load_dwordx4 v[0:3], v[8:9], off offset:2560
	global_load_dwordx4 v[4:7], v[12:13], off offset:2560
	s_nop 0
	global_load_dwordx4 v[8:11], v[8:9], off offset:2048
	s_nop 0
	global_load_dwordx4 v[12:15], v[12:13], off offset:2048
	v_lshlrev_b32_e32 v17, 3, v58
	v_and_b32_e32 v20, 0xfffff0, v70
	v_lshlrev_b32_e32 v21, 1, v70
	v_lshrrev_b32_e32 v22, 1, v70
	v_and_b32_e32 v23, 3, v70
	v_and_b32_e32 v19, 0x78, v17
	v_and_or_b32 v20, v21, 8, v20
	v_and_or_b32 v21, v22, 4, v23
	v_and_b32_e32 v22, 0xfffff0, v16
	v_lshlrev_b32_e32 v23, 1, v16
	v_and_b32_e32 v18, 0xf0, v58
	v_bfe_u32 v17, v17, 5, 2
	v_lshlrev_b32_e32 v24, 8, v70
	v_lshlrev_b32_e32 v19, 1, v19
	v_lshlrev_b32_e32 v16, 8, v16
	v_lshrrev_b32_e32 v20, 1, v20
	v_and_or_b32 v22, v23, 8, v22
	v_and_b32_e32 v25, 48, v19
	v_bitop3_b32 v23, v19, v24, v18 bitop3:0xde
	v_bitop3_b32 v16, v19, v16, v18 bitop3:0xde
	v_or_b32_e32 v18, v20, v17
	v_lshrrev_b32_e32 v19, 1, v22
	v_lshlrev_b32_e32 v21, 6, v21
	v_add_u32_e32 v196, 0, v16
	v_lshlrev_b32_e32 v16, 9, v18
	v_or_b32_e32 v17, v19, v17
	v_or3_b32 v16, v16, v21, v25
	v_lshlrev_b32_e32 v17, 9, v17
	v_and_b32_e32 v189, 31, v58
	v_lshlrev_b32_e32 v60, 4, v58
	v_or3_b32 v17, v17, v21, v25
	v_add_u32_e32 v197, 0, v16
	v_add_u32_e32 v195, 0, v23
	v_add_u32_e32 v198, 0, v17
	s_waitcnt vmcnt(0)
	v_lshl_add_u32 v61, v189, 8, 0
	v_and_b32_e32 v62, 0xf0, v60
	v_and_b32_e32 v71, 63, v58
	v_and_b32_e32 v63, 0x3fffffc0, v58
	v_lshlrev_b32_e32 v58, 1, v58
	v_and_b32_e32 v182, 0xffffffe0, v59
	v_lshlrev_b32_e32 v59, 3, v71
	v_and_b32_e32 v58, 32, v58
	v_lshl_add_u32 v183, v63, 2, s74
	v_mad_i64_i32 v[66:67], s[0:1], v70, s40, 0
	v_lshl_add_u32 v191, v189, 2, v183
	s_mov_b32 s61, -1
	s_waitcnt vmcnt(3)
	ds_write_b128 v197, v[0:3]
	s_waitcnt vmcnt(2)
	ds_write_b128 v198, v[4:7]
	s_waitcnt vmcnt(1)
	ds_write_b128 v195, v[8:11] offset:32768
	s_waitcnt vmcnt(0)
	ds_write_b128 v196, v[12:15] offset:32768
	v_bitop3_b32 v0, v176, v60, s43 bitop3:0x78
	v_add_u32_e32 v199, v61, v0
	s_waitcnt lgkmcnt(0)
	s_barrier
	ds_read_b128 v[0:3], v199 offset:32768
	ds_read_b128 v[4:7], v199 offset:40960
	s_waitcnt lgkmcnt(1)
	v_mfma_f32_32x32x16_bf16 v[32:47], v[0:3], v[124:127], 0
	v_bitop3_b32 v0, v176, v62, 32 bitop3:0x36
	v_add_u32_e32 v200, v61, v0
	v_and_b32_e32 v60, 0xc0, v60
	v_mov_b32_e32 v192, 0
	s_waitcnt lgkmcnt(0)
	v_mfma_f32_32x32x16_bf16 v[16:31], v[4:7], v[124:127], 0
	ds_read_b128 v[0:3], v200 offset:32768
	ds_read_b128 v[4:7], v200 offset:40960
	s_waitcnt lgkmcnt(1)
	v_mfma_f32_32x32x16_bf16 v[32:47], v[0:3], v[120:123], v[32:47]
	v_bitop3_b32 v0, v176, v62, 64 bitop3:0x36
	v_add_u32_e32 v201, v61, v0
	s_waitcnt lgkmcnt(0)
	v_mfma_f32_32x32x16_bf16 v[16:31], v[4:7], v[120:123], v[16:31]
	ds_read_b128 v[0:3], v201 offset:32768
	ds_read_b128 v[4:7], v201 offset:40960
	s_waitcnt lgkmcnt(1)
	v_mfma_f32_32x32x16_bf16 v[32:47], v[0:3], v[116:119], v[32:47]
	v_bitop3_b32 v0, v176, v62, s44 bitop3:0x36
	v_add_u32_e32 v202, v61, v0
	s_waitcnt lgkmcnt(0)
	v_mfma_f32_32x32x16_bf16 v[16:31], v[4:7], v[116:119], v[16:31]
	ds_read_b128 v[0:3], v202 offset:32768
	ds_read_b128 v[4:7], v202 offset:40960
	s_waitcnt lgkmcnt(1)
	v_mfma_f32_32x32x16_bf16 v[32:47], v[0:3], v[112:115], v[32:47]
	v_bitop3_b32 v0, v176, v62, s45 bitop3:0x36
	v_add_u32_e32 v203, v61, v0
	s_waitcnt lgkmcnt(0)
	v_mfma_f32_32x32x16_bf16 v[16:31], v[4:7], v[112:115], v[16:31]
	ds_read_b128 v[0:3], v203 offset:32768
	ds_read_b128 v[4:7], v203 offset:40960
	s_waitcnt lgkmcnt(1)
	v_mfma_f32_32x32x16_bf16 v[32:47], v[0:3], v[108:111], v[32:47]
	v_bitop3_b32 v0, v176, v62, s46 bitop3:0x36
	v_add_u32_e32 v204, v61, v0
	s_waitcnt lgkmcnt(0)
	v_mfma_f32_32x32x16_bf16 v[16:31], v[4:7], v[108:111], v[16:31]
	ds_read_b128 v[0:3], v204 offset:32768
	ds_read_b128 v[4:7], v204 offset:40960
	s_waitcnt lgkmcnt(1)
	v_mfma_f32_32x32x16_bf16 v[32:47], v[0:3], v[104:107], v[32:47]
	v_bitop3_b32 v0, v176, v62, s42 bitop3:0x36
	v_add_u32_e32 v205, v61, v0
	ds_read_b128 v[50:53], v205 offset:32768
	ds_read_b128 v[54:57], v205 offset:40960
	s_waitcnt lgkmcnt(1)
; #define SLOAD(i, k0) do { sr_[i].vs0 = *reinterpret_cast<const bf16x8*>(vptr + (size_t)((k0) + sr) * vstr); \
;     sr_[i].vs1 = *reinterpret_cast<const bf16x8*>(vptr + (size_t)((k0) + 32 + sr) * vstr); \
;     sr_[i].ks0 = *reinterpret_cast<const bf16x8*>(kptr + (size_t)((k0) + sr) * kstr); \
;     sr_[i].ks1 = *reinterpret_cast<const bf16x8*>(kptr + (size_t)((k0) + 32 + sr) * kstr); } while (0)
; #define SWRITE(b, i) do { *(LAS bf16x8*)(V_lds + (b) * SHM_V + vst0) = sr_[i].vs0;          \
;     *(LAS bf16x8*)(V_lds + (b) * SHM_V + vst1) = sr_[i].vs1; const int kc = sc * 2;               \
;     *(LAS bf16x8*)(K_lds + (b) * SHM_K + KSWZ(sr, kc)) = sr_[i].ks0;                       \
;     *(LAS bf16x8*)(K_lds + (b) * SHM_K + KSWZ(32 + sr, kc)) = sr_[i].ks1; } while (0)
; #define SWAIT() asm volatile("s_waitcnt vmcnt(4)" ::: "memory")
; __device__ __forceinline__ void partialSM(f32x16& p0, f32x16& p1, float& m_reg, float& mn, float& alpha, float C, float thr) {
;   float pmax = p0[0];
; #pragma unroll
;   for (int r = 1; r < 16; ++r) pmax = fmaxf(pmax, p0[r]);
; #pragma unroll
;   for (int r = 0; r < 16; ++r) pmax = fmaxf(pmax, p1[r]);
;   { auto rr = __builtin_amdgcn_permlane32_swap(__float_as_uint(pmax), __float_as_uint(pmax), false, false);
;     pmax = fmaxf(__uint_as_float(rr[0]), __uint_as_float(rr[1])); }
;   if (__builtin_expect(__all(pmax - m_reg <= thr), 1)) { mn = m_reg; alpha = 1.f; }
;   else { mn = fmaxf(m_reg, pmax); alpha = __builtin_amdgcn_exp2f((m_reg - mn) * C); m_reg = mn; }
;   const float mnC = -mn * C;
; #pragma unroll
;   for (int r = 0; r < 16; ++r) p0[r] = fmaf(p0[r], C, mnC);
; #pragma unroll
;   for (int r = 0; r < 16; ++r) p1[r] = fmaf(p1[r], C, mnC);
; #pragma unroll
;   for (int r = 0; r < 16; ++r) p0[r] = __builtin_amdgcn_exp2f(p0[r]);
; }
; template <int NDQ, int NDV> ...
;     ...
;   qkt<NDQ>(pA0, pA1, K_lds, qr, r32, hi); partialSM(pA0, pA1, m_reg, mnA, alA, Cs, thr);
;   SLOAD(SO, 64); if (2 < NT) SLOAD(SE, 128);
;   SWAIT(); SWRITE(1, SO); __syncthreads();
;   for (int j = 1; j + 1 < NT; j += 2) {
	v_mfma_f32_32x32x16_bf16 v[32:47], v[50:53], v[100:103], v[32:47]
	v_bitop3_b32 v50, v176, v62, s47 bitop3:0x36
	v_add_u32_e32 v206, v61, v50
	ds_read_b128 v[50:53], v206 offset:32768
	v_add_u32_e32 v61, 64, v70
	v_mfma_f32_32x32x16_bf16 v[16:31], v[4:7], v[104:107], v[16:31]
	v_mov_b64_e32 v[0:1], s[12:13]
	v_mov_b64_e32 v[14:15], s[26:27]
	v_mov_b64_e32 v[2:3], s[14:15]
	v_mov_b64_e32 v[4:5], s[16:17]
	v_mov_b64_e32 v[6:7], s[18:19]
	v_mov_b64_e32 v[8:9], s[20:21]
	v_mov_b64_e32 v[10:11], s[22:23]
	s_waitcnt lgkmcnt(1)
	v_mfma_f32_32x32x16_bf16 v[16:31], v[54:57], v[100:103], v[16:31]
	ds_read_b128 v[54:57], v206 offset:40960
	v_mov_b64_e32 v[12:13], s[24:25]
	s_waitcnt lgkmcnt(1)
	v_mfma_f32_32x32x16_bf16 v[32:47], v[50:53], v[96:99], v[32:47]
	v_and_or_b32 v50, v59, 24, v60
	v_and_b32_e32 v51, 0x100, v59
	v_or3_b32 v72, v50, v58, v51
	v_mad_i64_i32 v[58:59], s[0:1], v61, s40, v[48:49]
	global_load_dwordx4 v[50:53], v[58:59], off offset:2560
	v_add_u32_e32 v194, 0, v72
	s_waitcnt lgkmcnt(0)
	v_mfma_f32_32x32x16_bf16 v[16:31], v[54:57], v[96:99], v[16:31]
	s_nop 3
	v_max_f32_e32 v54, v33, v33
	v_max_f32_e32 v55, v32, v32
	v_max_f32_e32 v54, v55, v54
	v_max3_f32 v54, v54, v34, v35
	v_max3_f32 v54, v54, v36, v37
	v_max3_f32 v54, v54, v38, v39
	v_max3_f32 v54, v54, v40, v41
	v_max3_f32 v54, v54, v42, v43
	v_max3_f32 v54, v54, v44, v45
	v_max3_f32 v54, v54, v46, v47
	v_max3_f32 v68, v54, v16, v17
	v_max3_f32 v68, v68, v18, v19
	v_max3_f32 v68, v68, v20, v21
	v_max3_f32 v68, v68, v22, v23
	v_max3_f32 v68, v68, v24, v25
	v_max3_f32 v68, v68, v26, v27
	v_add_u32_e32 v54, 0x60, v70
	v_max3_f32 v73, v68, v28, v29
	v_add_u32_e32 v68, 0xa0, v70
	v_mad_i64_i32 v[62:63], s[0:1], v54, s40, v[48:49]
	v_mad_i64_i32 v[68:69], s[0:1], v68, s40, v[48:49]
	v_add_u32_e32 v70, 0x80, v70
	global_load_dwordx4 v[54:57], v[62:63], off offset:2560
	s_nop 0
	global_load_dwordx4 v[58:61], v[58:59], off offset:2048
	s_nop 0
	global_load_dwordx4 v[62:65], v[62:63], off offset:2048
	v_mad_i64_i32 v[48:49], s[0:1], v70, s40, v[48:49]
	global_load_dwordx4 v[132:135], v[68:69], off offset:2048
	global_load_dwordx4 v[136:139], v[68:69], off offset:2560
	global_load_dwordx4 v[140:143], v[48:49], off offset:2048
	global_load_dwordx4 v[128:131], v[48:49], off offset:2560
	v_max3_f32 v48, v73, v30, v31
	v_mov_b32_e32 v49, v48
	s_nop 1
	v_permlane32_swap_b32_e32 v48, v49
	v_max_f32_e32 v49, v49, v49
	v_max_f32_e32 v48, v48, v48
	v_max_f32_e32 v48, v48, v49
	v_add_f32_e32 v49, 0x7149f2ca, v48
	v_max_f32_e32 v48, 0xf149f2ca, v48
	v_cmp_ge_f32_e32 vcc, s48, v49
	v_sub_f32_e32 v49, 0xf149f2ca, v48
	v_mul_f32_e32 v49, 0x3e0293ee, v49
	v_exp_f32_e32 v49, v49
	s_cmp_eq_u64 vcc, exec
	s_cselect_b64 vcc, -1, 0
	v_cndmask_b32_e32 v160, v48, v186, vcc
	v_mul_f32_e32 v48, 0xbe0293ee, v160
	v_cndmask_b32_e64 v207, v49, 1.0, vcc
	v_mov_b32_e32 v49, v48
	v_fmamk_f32 v32, v32, 0x3e0293ee, v48
	v_fmamk_f32 v33, v33, 0x3e0293ee, v48
	v_fmamk_f32 v34, v34, 0x3e0293ee, v48
	v_fmamk_f32 v35, v35, 0x3e0293ee, v48
	v_fmamk_f32 v36, v36, 0x3e0293ee, v48
	v_fmamk_f32 v37, v37, 0x3e0293ee, v48
	v_fmamk_f32 v38, v38, 0x3e0293ee, v48
	v_fmamk_f32 v39, v39, 0x3e0293ee, v48
	v_fmamk_f32 v40, v40, 0x3e0293ee, v48
	v_fmamk_f32 v41, v41, 0x3e0293ee, v48
	v_fmamk_f32 v42, v42, 0x3e0293ee, v48
	v_fmamk_f32 v43, v43, 0x3e0293ee, v48
	v_fmamk_f32 v44, v44, 0x3e0293ee, v48
	v_fmamk_f32 v45, v45, 0x3e0293ee, v48
	v_fmamk_f32 v46, v46, 0x3e0293ee, v48
	v_fmac_f32_e32 v49, 0x3e0293ee, v47
	v_pk_fma_f32 v[154:155], v[16:17], s[4:5], v[48:49] op_sel_hi:[1,0,0]
	v_exp_f32_e32 v175, v32
	v_exp_f32_e32 v214, v33
	v_exp_f32_e32 v173, v34
	v_exp_f32_e32 v211, v35
	v_exp_f32_e32 v172, v36
	v_exp_f32_e32 v174, v37
	v_exp_f32_e32 v170, v38
	v_exp_f32_e32 v171, v39
	v_exp_f32_e32 v167, v40
	v_exp_f32_e32 v169, v41
	v_exp_f32_e32 v166, v42
	v_exp_f32_e32 v168, v43
	v_exp_f32_e32 v163, v44
	v_exp_f32_e32 v165, v45
	v_exp_f32_e32 v162, v46
	v_exp_f32_e32 v164, v49
	v_mad_i64_i32 v[16:17], s[30:31], s3, v187, v[66:67]
	s_waitcnt vmcnt(4)
	v_lshl_or_b32 v16, s2, 6, v16
	v_pk_fma_f32 v[150:151], v[30:31], s[4:5], v[48:49] op_sel_hi:[1,0,0]
	v_pk_fma_f32 v[156:157], v[28:29], s[4:5], v[48:49] op_sel_hi:[1,0,0]
	v_pk_fma_f32 v[158:159], v[26:27], s[4:5], v[48:49] op_sel_hi:[1,0,0]
	v_pk_fma_f32 v[144:145], v[24:25], s[4:5], v[48:49] op_sel_hi:[1,0,0]
	v_pk_fma_f32 v[146:147], v[22:23], s[4:5], v[48:49] op_sel_hi:[1,0,0]
	v_pk_fma_f32 v[148:149], v[20:21], s[4:5], v[48:49] op_sel_hi:[1,0,0]
	v_pk_fma_f32 v[152:153], v[18:19], s[4:5], v[48:49] op_sel_hi:[1,0,0]
	s_waitcnt vmcnt(7)
	ds_write_b128 v197, v[50:53] offset:16384
	s_waitcnt vmcnt(6)
	ds_write_b128 v198, v[54:57] offset:16384
	s_waitcnt vmcnt(5)
	ds_write_b128 v195, v[58:61] offset:49152
	s_waitcnt vmcnt(4)
	ds_write_b128 v196, v[62:65] offset:49152
	v_lshl_add_u64 v[184:185], v[178:179], 0, v[16:17]
	v_mov_b64_e32 v[62:63], v[14:15]
	v_mov_b64_e32 v[46:47], v[14:15]
	v_mov_b64_e32 v[30:31], v[14:15]
	v_cmp_gt_u32_e64 s[0:1], 32, v71
	v_add_u32_e32 v193, s75, v72
	v_mov_b64_e32 v[60:61], v[12:13]
	v_mov_b64_e32 v[58:59], v[10:11]
	v_mov_b64_e32 v[56:57], v[8:9]
	v_mov_b64_e32 v[54:55], v[6:7]
	v_mov_b64_e32 v[52:53], v[4:5]
	v_mov_b64_e32 v[50:51], v[2:3]
	v_mov_b64_e32 v[48:49], v[0:1]
	v_mov_b64_e32 v[44:45], v[12:13]
	v_mov_b64_e32 v[42:43], v[10:11]
	v_mov_b64_e32 v[40:41], v[8:9]
	v_mov_b64_e32 v[38:39], v[6:7]
	v_mov_b64_e32 v[36:37], v[4:5]
	v_mov_b64_e32 v[34:35], v[2:3]
	v_mov_b64_e32 v[32:33], v[0:1]
	v_mov_b64_e32 v[28:29], v[12:13]
	v_mov_b64_e32 v[26:27], v[10:11]
	v_mov_b64_e32 v[24:25], v[8:9]
	v_mov_b64_e32 v[22:23], v[6:7]
	v_mov_b64_e32 v[20:21], v[4:5]
	v_mov_b64_e32 v[18:19], v[2:3]
	v_mov_b64_e32 v[16:17], v[0:1]
	v_mov_b32_e32 v236, v175
	v_mov_b32_e32 v237, v214
	v_mov_b32_e32 v238, v173
	v_mov_b32_e32 v239, v211
	v_mov_b32_e32 v240, v172
	v_mov_b32_e32 v241, v174
	v_mov_b32_e32 v242, v170
	v_mov_b32_e32 v243, v171
	v_mov_b32_e32 v244, v167
	v_mov_b32_e32 v245, v169
	v_mov_b32_e32 v246, v166
	v_mov_b32_e32 v247, v168
	v_mov_b32_e32 v248, v163
	v_mov_b32_e32 v249, v165
	v_mov_b32_e32 v250, v162
	v_mov_b32_e32 v251, v164
	s_waitcnt lgkmcnt(0)
	s_barrier
	.p2align	6
